# diff-attention unit prologue de-serialised: tile-1 K/V loads issued together with tile-0's into spare registers (one exposed memory latency per unit instead of two)
# baseline (speedup 1.0000x reference)
; template <int NMAP, int VD, bool SWA> ...
;     ...
;     { const bf16_t* qr = Qp + (size_t)(16 * w + fr) * qpitch + fq * 8;
; #pragma unroll
;       for (int mp = 0; mp < NMAP; ++mp)
; #pragma unroll
;           for (int ks = 0; ks < 2; ++ks) qf[mp][ks] = *(const bf16x8*)(qr + mp * 64 + ks * 32); }
;     f32x4 oacc[NMAP][NET], negm[NMAP]; float mrun[NMAP], lsum[NMAP];
; #pragma unroll
;     for (int mp = 0; mp < NMAP; ++mp) { mrun[mp] = 0.f; lsum[mp] = 0.f; negm[mp] = (f32x4){0.f, 0.f, 0.f, 0.f};
; #pragma unroll
;         for (int et = 0; et < NET; ++et) oacc[mp][et] = (f32x4){0.f, 0.f, 0.f, 0.f}; }
;     const int ntiles = n0 + (t1hi - t1lo);
;     u32x4 kreg[NKC], vreg[NVC];
;     ...
;     ATT_LOAD(ATT_TILE(0));
;     ATT_STORE(0);
;     if (ntiles > 1) ATT_LOAD(ATT_TILE(1));
;     __syncthreads();
.LBB0_121:
	s_and_b32 s0, s22, 0xffffff00
	s_cmpk_eq_i32 s0, 0x200
	s_cselect_b64 s[0:1], -1, 0
	s_cmp_ge_i32 s22, s13
	s_cselect_b64 s[8:9], -1, 0
	s_or_b64 s[10:11], s[8:9], s[0:1]
	s_cmpk_gt_i32 s22, 0x2ff
	s_mov_b64 s[8:9], -1
	s_cselect_b64 s[0:1], -1, 0
	s_and_b64 vcc, exec, s[10:11]
	v_ashrrev_i32_e32 v178, 31, v176
	v_lshlrev_b32_e32 v175, 2, v177
	s_cbranch_vccnz .LBB0_139
	s_ashr_i32 s21, s20, 31
	s_lshl_b64 s[8:9], s[20:21], 10
	v_readlane_b32 s3, v252, 43
	s_add_u32 s3, s3, s8
	v_readlane_b32 s8, v252, 44
	s_addc_u32 s8, s8, s9
	s_lshl_b32 s25, s16, 7
	s_lshl_b32 s9, s16, 8
	s_waitcnt vmcnt(0) lgkmcnt(0)
	v_add_u32_e32 v22, 0x200, v176
	s_add_u32 s28, s3, s9
	v_lshrrev_b32_e32 v0, 28, v178
	v_ashrrev_i32_e32 v23, 31, v22
	s_addc_u32 s29, s8, 0
	s_lshl_b32 s14, s24, 2
	v_add_u32_e32 v0, v176, v0
	v_lshrrev_b32_e32 v23, 28, v23
	s_add_i32 s14, s14, s16
	v_ashrrev_i32_e32 v34, 4, v0
	v_add_u32_e32 v23, v22, v23
	s_mul_i32 s8, s14, 0x90000
	v_readlane_b32 s9, v252, 47
	v_and_b32_e32 v0, -16, v0
	v_ashrrev_i32_e32 v35, 31, v34
	v_ashrrev_i32_e32 v36, 4, v23
	v_and_b32_e32 v23, -16, v23
	s_mul_hi_i32 s3, s14, 0x90000
	s_add_u32 s10, s9, s8
	v_readlane_b32 s9, v252, 48
	v_sub_u32_e32 v0, v176, v0
	v_lshlrev_b64 v[58:59], 8, v[34:35]
	v_sub_u32_e32 v35, v22, v23
	s_addc_u32 s11, s9, s3
	v_readlane_b32 s9, v252, 49
	v_ashrrev_i32_e32 v161, 31, v160
	v_lshlrev_b32_e32 v20, 3, v0
	v_ashrrev_i32_e32 v37, 31, v36
	v_lshlrev_b32_e32 v24, 3, v35
	s_add_u32 s8, s9, s8
	v_readlane_b32 s9, v252, 50
	v_lshlrev_b64 v[2:3], 10, v[160:161]
	v_ashrrev_i32_e32 v21, 31, v20
	v_lshlrev_b64 v[94:95], 8, v[36:37]
	v_ashrrev_i32_e32 v25, 31, v24
	s_addc_u32 s9, s9, s3
	v_lshl_add_u64 v[2:3], s[28:29], 0, v[2:3]
	v_mov_b32_e32 v163, v1
	v_lshl_add_u64 v[18:19], s[10:11], 0, v[58:59]
	v_lshlrev_b64 v[60:61], 1, v[20:21]
	v_lshl_add_u64 v[22:23], s[10:11], 0, v[94:95]
	v_lshlrev_b64 v[96:97], 1, v[24:25]
	v_lshl_add_u64 v[2:3], v[2:3], 0, v[162:163]
	s_mov_b64 s[34:35], 0x4000
	v_lshl_add_u64 v[18:19], v[18:19], 0, v[60:61]
	v_lshl_add_u64 v[22:23], v[22:23], 0, v[96:97]
	v_lshl_add_u64 v[236:237], v[18:19], 0, s[34:35]
	v_lshl_add_u64 v[240:241], v[22:23], 0, s[34:35]
	v_lshl_add_u64 v[26:27], s[8:9], 0, v[58:59]
	global_load_dwordx4 v[14:17], v[2:3], off
	global_load_dwordx4 v[10:13], v[2:3], off offset:64
	global_load_dwordx4 v[6:9], v[2:3], off offset:128
	s_nop 0
	global_load_dwordx4 v[2:5], v[2:3], off offset:192
	v_lshl_add_u64 v[26:27], v[26:27], 0, v[60:61]
	v_lshl_add_u64 v[244:245], v[26:27], 0, s[34:35]
	global_load_dwordx4 v[18:21], v[18:19], off
	v_lshl_add_u64 v[30:31], s[8:9], 0, v[94:95]
	global_load_dwordx4 v[22:25], v[22:23], off
	v_lshl_add_u64 v[30:31], v[30:31], 0, v[96:97]
	v_lshl_add_u64 v[248:249], v[30:31], 0, s[34:35]
	global_load_dwordx4 v[26:29], v[26:27], off
	s_movk_i32 s15, 0x120
	global_load_dwordx4 v[30:33], v[30:31], off
	global_load_dwordx4 v[236:239], v[236:237], off
	global_load_dwordx4 v[240:243], v[240:241], off
	global_load_dwordx4 v[244:247], v[244:245], off
	global_load_dwordx4 v[248:251], v[248:249], off
	v_mul_lo_u32 v208, v34, s15
	v_lshlrev_b32_e32 v209, 4, v0
	v_mul_lo_u32 v210, v36, s15
	v_lshlrev_b32_e32 v211, 4, v35
	v_add3_u32 v34, 0, v208, v209
	v_add3_u32 v35, 0, v210, v211
	s_mov_b64 s[34:35], 0x4000
	v_lshlrev_b32_e32 v36, 2, v176
	v_and_b32_e32 v56, 12, v36
	v_mbcnt_hi_u32_b32 v36, -1, v190
	v_and_b32_e32 v38, 64, v36
	v_xor_b32_e32 v37, 16, v36
	v_add_u32_e32 v38, 64, v38
	v_cmp_lt_i32_e32 vcc, v37, v38
	v_mul_u32_u24_e32 v182, 0x120, v173
	v_add3_u32 v57, 0, v162, v182
	v_cndmask_b32_e32 v37, v36, v37, vcc
	v_lshlrev_b32_e32 v179, 2, v37
	v_xor_b32_e32 v37, 32, v36
	v_cmp_lt_i32_e32 vcc, v37, v38
	v_readlane_b32 s28, v254, 39
	v_readlane_b32 s29, v254, 40
	v_cndmask_b32_e32 v36, v36, v37, vcc
	v_lshlrev_b32_e32 v180, 2, v36
	v_lshlrev_b32_e32 v163, 2, v177
	v_bfe_u32 v0, v176, 2, 2
	s_mov_b32 s26, s28
	v_readlane_b32 s28, v254, 43
	v_or_b32_e32 v0, v163, v0
	v_readlane_b32 s29, v254, 44
	v_lshlrev_b32_e32 v107, 3, v177
	s_mov_b32 s3, 1
	v_mul_u32_u24_e32 v0, 0x120, v0
	s_waitcnt vmcnt(7)
	ds_write_b128 v34, v[18:21]
	s_waitcnt vmcnt(6)
	ds_write_b128 v35, v[22:25]
	s_waitcnt vmcnt(5)
	ds_write_b128 v34, v[26:29] offset:18432
	s_waitcnt vmcnt(4)
	ds_write_b128 v35, v[30:33] offset:18432
	s_mov_b64 s[34:35], 0x8000
	s_waitcnt lgkmcnt(0)
	s_barrier
; #define LAS __attribute__((address_space(3)))
; template <int NMAP, int VD, bool SWA> ...
;     ...
;     for (int i = 0; i < ntiles; ++i) {
;         const int t = ATT_TILE(i);
;         if (i + 1 < ntiles) { ATT_STORE((i + 1) & 1); if (i + 2 < ntiles) ATT_LOAD(ATT_TILE(i + 2)); }
;         const LAS bf16_t* kS = (const LAS bf16_t*)(lds + (i & 1) * BUFB);
;         const LAS bf16_t* vS = (const LAS bf16_t*)(lds + (i & 1) * BUFB + KBYTES);
;         bf16x8 pf[NMAP][2];
;         f32x4 sacc[NMAP][4];
; #pragma unroll
;         for (int mp = 0; mp < NMAP; ++mp) {
;             bf16x8 kf[4][2];
; #pragma unroll
;             for (int kt = 0; kt < 4; ++kt)
; #pragma unroll
;                 for (int ks = 0; ks < 2; ++ks) kf[kt][ks] = *(const LAS bf16x8*)(kS + (16 * kt + fr) * KP + mp * KMS + ks * 32 + fq * 8);
;             __builtin_amdgcn_sched_barrier(0);
; #pragma unroll
;             for (int kt = 0; kt < 4; ++kt) sacc[mp][kt] = __builtin_amdgcn_mfma_f32_16x16x32_bf16(kf[kt][0], qf[mp][0], negm[mp], 0, 0, 0);
; #pragma unroll
;             for (int kt = 0; kt < 4; ++kt) sacc[mp][kt] = __builtin_amdgcn_mfma_f32_16x16x32_bf16(kf[kt][1], qf[mp][1], sacc[mp][kt], 0, 0, 0);
;         }
;         bf16x8 va[4];
;     ...
; #pragma unroll
;         for (int i2 = 0; i2 < 4; ++i2) ATT_LDV(va[i2], i2);
;         if (SWA && t >= 4) {
;             const int dq = qp0 + 16 * w + fr - (64 * (t - 4) + 4 * fq);
; #pragma unroll
;             for (int kt = 0; kt < 4; ++kt)
; #pragma unroll
;                 for (int r = 0; r < 4; ++r) { const int d = dq - 16 * kt - r; if (d > 128 || d < -128) {
; #pragma unroll
;                     for (int mp = 0; mp < NMAP; ++mp) sacc[mp][kt][r] = -INFINITY; } }
;         }
;         float mx[NMAP];
; #pragma unroll
;         for (int mp = 0; mp < NMAP; ++mp) {
;             float v = fmax2(fmax2(sacc[mp][0][0], sacc[mp][0][1]), fmax2(sacc[mp][0][2], sacc[mp][0][3]));
; #pragma unroll
;             for (int kt = 1; kt < 4; ++kt) v = fmax2(v, fmax2(fmax2(sacc[mp][kt][0], sacc[mp][kt][1]), fmax2(sacc[mp][kt][2], sacc[mp][kt][3])));
;             mx[mp] = v;
;         }
; #pragma unroll
;         for (int mp = 0; mp < NMAP; ++mp) mx[mp] = fmax2(mx[mp], __shfl_xor(mx[mp], 16));
; #pragma unroll
;         for (int mp = 0; mp < NMAP; ++mp) mx[mp] = fmax2(mx[mp], __shfl_xor(mx[mp], 32));
; #pragma unroll
;         for (int mp = 0; mp < NMAP; ++mp) {
	s_waitcnt vmcnt(3)
	ds_write_b128 v34, v[236:239] offset:36864
	s_waitcnt vmcnt(2)
	ds_write_b128 v35, v[240:243] offset:36864
	s_waitcnt vmcnt(1)
	ds_write_b128 v34, v[244:247] offset:55296
	s_waitcnt vmcnt(0)
	ds_write_b128 v35, v[248:251] offset:55296
	v_lshl_add_u64 v[18:19], v[58:59], 0, s[34:35]
	v_lshl_add_u64 v[20:21], s[10:11], 0, v[18:19]
	v_lshl_add_u64 v[18:19], s[8:9], 0, v[18:19]
	v_lshl_add_u64 v[20:21], v[20:21], 0, v[60:61]
	v_lshl_add_u64 v[18:19], v[18:19], 0, v[60:61]
	global_load_dwordx4 v[86:89], v[20:21], off
	global_load_dwordx4 v[98:101], v[18:19], off
	v_lshl_add_u64 v[20:21], v[94:95], 0, s[34:35]
	v_lshl_add_u64 v[22:23], s[10:11], 0, v[20:21]
	v_lshl_add_u64 v[18:19], s[8:9], 0, v[20:21]
	v_lshl_add_u64 v[22:23], v[22:23], 0, v[96:97]
	v_lshl_add_u64 v[18:19], v[18:19], 0, v[96:97]
	global_load_dwordx4 v[90:93], v[22:23], off
	global_load_dwordx4 v[102:105], v[18:19], off
	ds_read_b128 v[18:21], v57
	ds_read_b128 v[22:25], v57 offset:64
	ds_read_b128 v[26:29], v57 offset:4608
	ds_read_b128 v[30:33], v57 offset:4672
	ds_read_b128 v[34:37], v57 offset:9216
	ds_read_b128 v[38:41], v57 offset:9280
	ds_read_b128 v[42:45], v57 offset:13824
	ds_read_b128 v[46:49], v57 offset:13888
	s_waitcnt lgkmcnt(7)
	v_mfma_f32_16x16x32_bf16 v[18:21], v[18:21], v[14:17], 0
	s_waitcnt lgkmcnt(5)
	v_mfma_f32_16x16x32_bf16 v[26:29], v[26:29], v[14:17], 0
	s_waitcnt lgkmcnt(3)
	v_mfma_f32_16x16x32_bf16 v[34:37], v[34:37], v[14:17], 0
	s_waitcnt lgkmcnt(1)
	v_mfma_f32_16x16x32_bf16 v[42:45], v[42:45], v[14:17], 0
	v_mfma_f32_16x16x32_bf16 v[18:21], v[22:25], v[10:13], v[18:21]
	v_mfma_f32_16x16x32_bf16 v[24:27], v[30:33], v[10:13], v[26:29]
	v_mfma_f32_16x16x32_bf16 v[28:31], v[38:41], v[10:13], v[34:37]
	s_waitcnt lgkmcnt(0)
	v_mfma_f32_16x16x32_bf16 v[32:35], v[46:49], v[10:13], v[42:45]
	s_nop 0
	ds_read_b128 v[36:39], v57 offset:128
	s_nop 0
	ds_read_b128 v[40:43], v57 offset:192
	ds_read_b128 v[44:47], v57 offset:4736
	ds_read_b128 v[48:51], v57 offset:4800
	ds_read_b128 v[52:55], v57 offset:9344
	ds_read_b128 v[62:65], v57 offset:9408
	ds_read_b128 v[66:69], v57 offset:13952
	ds_read_b128 v[70:73], v57 offset:14016
	v_lshlrev_b32_e32 v181, 1, v56
	v_med3_f32 v23, v18, v19, s27
	v_med3_f32 v56, v20, v21, s27
	s_waitcnt lgkmcnt(7)
	v_mfma_f32_16x16x32_bf16 v[36:39], v[36:39], v[6:9], 0
	v_med3_f32 v23, v23, v56, s27
	v_med3_f32 v56, v24, v25, s27
	v_med3_f32 v57, v26, v27, s27
	v_med3_f32 v56, v56, v57, s27
	s_waitcnt lgkmcnt(5)
	v_mfma_f32_16x16x32_bf16 v[44:47], v[44:47], v[6:9], 0
	v_med3_f32 v23, v23, v56, s27
	v_med3_f32 v56, v28, v29, s27
	v_med3_f32 v57, v30, v31, s27
	v_med3_f32 v56, v56, v57, s27
	v_med3_f32 v23, v23, v56, s27
	v_med3_f32 v56, v32, v33, s27
	v_mfma_f32_16x16x32_bf16 v[36:39], v[40:43], v[2:5], v[36:39]
	v_med3_f32 v40, v34, v35, s27
	v_med3_f32 v40, v56, v40, s27
	v_med3_f32 v23, v23, v40, s27
	s_waitcnt lgkmcnt(3)
	v_mfma_f32_16x16x32_bf16 v[52:55], v[52:55], v[6:9], 0
	v_add3_u32 v22, 0, v0, v181
	v_mad_i64_i32 v[58:59], s[8:9], s14, v192, v[58:59]
	v_mfma_f32_16x16x32_bf16 v[40:43], v[48:51], v[2:5], v[44:47]
	v_lshl_add_u64 v[58:59], v[58:59], 0, v[60:61]
	s_and_b64 s[8:9], s[0:1], exec
	s_cselect_b32 s10, 1, 33
	s_waitcnt lgkmcnt(1)
	v_mfma_f32_16x16x32_bf16 v[66:69], v[66:69], v[6:9], 0
	v_med3_f32 v44, v36, v37, s27
	v_med3_f32 v45, v38, v39, s27
	v_med3_f32 v56, v44, v45, s27
	v_mfma_f32_16x16x32_bf16 v[44:47], v[62:65], v[2:5], v[52:55]
	v_med3_f32 v48, v40, v41, s27
	v_med3_f32 v49, v42, v43, s27
	s_lshl_b32 s11, s10, 14
	v_med3_f32 v52, v48, v49, s27
	s_waitcnt lgkmcnt(0)
	v_mfma_f32_16x16x32_bf16 v[48:51], v[70:73], v[2:5], v[66:69]
	s_nop 1
	v_med3_f32 v53, v44, v45, s27
	v_med3_f32 v54, v46, v47, s27
	v_med3_f32 v52, v56, v52, s27
	v_med3_f32 v53, v53, v54, s27
	v_med3_f32 v52, v52, v53, s27
	s_nop 0
	v_med3_f32 v53, v48, v49, s27
	v_med3_f32 v54, v50, v51, s27
	v_med3_f32 v53, v53, v54, s27
	v_med3_f32 v54, v52, v53, s27
	ds_bpermute_b32 v55, v179, v23
	ds_bpermute_b32 v56, v179, v54
	ds_read_b64_tr_b16 v[52:53], v22 offset:18432
	ds_read_b64_tr_b16 v[62:63], v22 offset:18464
	ds_read_b64_tr_b16 v[66:67], v22 offset:18496
	ds_read_b64_tr_b16 v[70:71], v22 offset:18528
	s_waitcnt lgkmcnt(5)
	v_med3_f32 v23, v23, v55, s27
	s_waitcnt lgkmcnt(4)
	v_med3_f32 v56, v54, v56, s27
	ds_bpermute_b32 v57, v180, v23
	ds_bpermute_b32 v74, v180, v56
	ds_read_b64_tr_b16 v[54:55], v22 offset:23040
	ds_read_b64_tr_b16 v[64:65], v22 offset:23072
	ds_read_b64_tr_b16 v[68:69], v22 offset:23104
	ds_read_b64_tr_b16 v[72:73], v22 offset:23136
	s_waitcnt lgkmcnt(5)
	v_med3_f32 v23, v23, v57, s27
	s_waitcnt lgkmcnt(4)
	v_med3_f32 v109, v56, v74, s27
	v_sub_f32_e32 v35, v35, v23
	v_sub_f32_e32 v34, v34, v23
	v_sub_f32_e32 v33, v33, v23
	v_sub_f32_e32 v32, v32, v23
	v_sub_f32_e32 v31, v31, v23
	v_sub_f32_e32 v30, v30, v23
	v_sub_f32_e32 v29, v29, v23
	v_sub_f32_e32 v28, v28, v23
	v_sub_f32_e32 v27, v27, v23
	v_sub_f32_e32 v26, v26, v23
	v_sub_f32_e32 v25, v25, v23
	v_sub_f32_e32 v24, v24, v23
	v_sub_f32_e32 v21, v21, v23
	v_sub_f32_e32 v20, v20, v23
	v_sub_f32_e32 v19, v19, v23
	v_sub_f32_e32 v18, v18, v23
	v_exp_f32_e32 v111, v28
	v_exp_f32_e32 v156, v29
	v_exp_f32_e32 v157, v30
	v_exp_f32_e32 v164, v31
	v_exp_f32_e32 v165, v32
	v_exp_f32_e32 v166, v33
	v_exp_f32_e32 v167, v34
	v_exp_f32_e32 v183, v35
	v_sub_f32_e32 v28, v43, v109
	v_sub_f32_e32 v29, v42, v109
	v_sub_f32_e32 v30, v41, v109
	v_sub_f32_e32 v31, v40, v109
	v_sub_f32_e32 v32, v39, v109
	v_sub_f32_e32 v33, v38, v109
	v_sub_f32_e32 v34, v37, v109
	v_sub_f32_e32 v35, v36, v109
	v_exp_f32_e32 v56, v18
	v_exp_f32_e32 v57, v19
	v_exp_f32_e32 v74, v20
	v_exp_f32_e32 v75, v21
	v_exp_f32_e32 v76, v24
	v_exp_f32_e32 v106, v25
	v_exp_f32_e32 v108, v26
	v_exp_f32_e32 v110, v27
	v_cvt_pk_bf16_f32 v24, v56, v57
	v_cvt_pk_bf16_f32 v25, v74, v75
	v_cvt_pk_bf16_f32 v26, v76, v106
	v_cvt_pk_bf16_f32 v27, v108, v110
	v_cvt_pk_bf16_f32 v18, v111, v156
	v_cvt_pk_bf16_f32 v19, v157, v164
	v_cvt_pk_bf16_f32 v20, v165, v166
	v_cvt_pk_bf16_f32 v21, v167, v183
	v_sub_f32_e32 v77, v51, v109
	v_sub_f32_e32 v78, v50, v109
	v_sub_f32_e32 v79, v49, v109
	v_exp_f32_e32 v202, v35
	v_exp_f32_e32 v203, v34
	v_exp_f32_e32 v212, v33
	v_exp_f32_e32 v213, v32
	v_exp_f32_e32 v214, v31
	v_exp_f32_e32 v215, v30
	v_exp_f32_e32 v216, v29
	v_exp_f32_e32 v217, v28
	v_cvt_pk_bf16_f32 v28, v202, v203
	s_waitcnt lgkmcnt(3)
; __device__ __forceinline__ unsigned cvt_pk_bf16(float lo, float hi) { unsigned r; asm volatile("v_cvt_pk_bf16_f32 %0, %1, %2" : "=v"(r) : "v"(lo), "v"(hi)); return r; }
; template <int NMAP, int VD, bool SWA> ...
;     ...
;                 for (int r = 0; r < 4; ++r) { const float p = __builtin_amdgcn_exp2f(sacc[mp][kt][r]); sacc[mp][kt][r] = p; ps += p; }
;             lsum[mp] += ps;
; #pragma unroll
;             for (int s2 = 0; s2 < 2; ++s2) {
;                 u32x4 pk; pk.x = cvt_pk_bf16(sacc[mp][2 * s2][0], sacc[mp][2 * s2][1]); pk.y = cvt_pk_bf16(sacc[mp][2 * s2][2], sacc[mp][2 * s2][3]);
;                 pk.z = cvt_pk_bf16(sacc[mp][2 * s2 + 1][0], sacc[mp][2 * s2 + 1][1]); pk.w = cvt_pk_bf16(sacc[mp][2 * s2 + 1][2], sacc[mp][2 * s2 + 1][3]);
;                 pf[mp][s2] = __builtin_bit_cast(bf16x8, pk);
;             }
;         }
; #pragma unroll
;         for (int idx = 0; idx < 2 * NET; ++idx) {
;             const int et = idx % NET, s2 = idx / NET;
;             const bf16x8 cur = va[idx & 3];
;             if (idx + 4 < 2 * NET) ATT_LDV(va[idx & 3], idx + 4);
; #pragma unroll
;             for (int mp = 0; mp < NMAP; ++mp) oacc[mp][et] = __builtin_amdgcn_mfma_f32_16x16x32_bf16(cur, pf[mp][s2], oacc[mp][et], 0, 0, 0);
;         }
;     ...
;         __syncthreads();
	v_mfma_f32_16x16x32_bf16 v[32:35], v[52:55], v[24:27], 0
	v_cvt_pk_bf16_f32 v29, v212, v213
	v_cvt_pk_bf16_f32 v30, v214, v215
	v_cvt_pk_bf16_f32 v31, v216, v217
	v_sub_f32_e32 v49, v46, v109
	v_mfma_f32_16x16x32_bf16 v[36:39], v[52:55], v[28:31], 0
	v_sub_f32_e32 v52, v48, v109
	v_sub_f32_e32 v48, v47, v109
	v_sub_f32_e32 v50, v45, v109
	v_sub_f32_e32 v44, v44, v109
	s_waitcnt lgkmcnt(2)
	v_mfma_f32_16x16x32_bf16 v[40:43], v[62:65], v[24:27], 0
	v_exp_f32_e32 v218, v44
	v_exp_f32_e32 v219, v50
	v_exp_f32_e32 v220, v49
	v_mfma_f32_16x16x32_bf16 v[44:47], v[62:65], v[28:31], 0
	v_exp_f32_e32 v221, v48
	v_exp_f32_e32 v222, v52
	v_exp_f32_e32 v223, v79
	v_exp_f32_e32 v224, v78
	v_exp_f32_e32 v225, v77
	v_cvt_pk_bf16_f32 v112, v218, v219
	v_cvt_pk_bf16_f32 v113, v220, v221
	v_cvt_pk_bf16_f32 v114, v222, v223
	v_cvt_pk_bf16_f32 v115, v224, v225
	ds_read_b64_tr_b16 v[64:65], v22 offset:23168
	ds_read_b64_tr_b16 v[62:63], v22 offset:18560
	s_waitcnt lgkmcnt(3)
	v_mfma_f32_16x16x32_bf16 v[48:51], v[66:69], v[24:27], 0
	v_mfma_f32_16x16x32_bf16 v[52:55], v[66:69], v[28:31], 0
	ds_read_b64_tr_b16 v[68:69], v22 offset:23200
	ds_read_b64_tr_b16 v[66:67], v22 offset:18592
	s_waitcnt lgkmcnt(2)
	v_mfma_f32_16x16x32_bf16 v[124:127], v[62:65], v[24:27], 0
	v_mfma_f32_16x16x32_bf16 v[128:131], v[62:65], v[28:31], 0
	ds_read_b64_tr_b16 v[62:63], v22 offset:18624
	ds_read_b64_tr_b16 v[64:65], v22 offset:23232
	s_waitcnt lgkmcnt(2)
	v_mfma_f32_16x16x32_bf16 v[132:135], v[66:69], v[24:27], 0
	v_mfma_f32_16x16x32_bf16 v[136:139], v[66:69], v[28:31], 0
	ds_read_b64_tr_b16 v[66:67], v22 offset:18656
	s_waitcnt lgkmcnt(1)
	v_mfma_f32_16x16x32_bf16 v[140:143], v[62:65], v[24:27], 0
	v_mfma_f32_16x16x32_bf16 v[144:147], v[62:65], v[28:31], 0
	ds_read_b64_tr_b16 v[68:69], v22 offset:23264
	ds_read_b64_tr_b16 v[62:63], v22 offset:27648
	v_mfma_f32_16x16x32_bf16 v[116:119], v[70:73], v[24:27], 0
	s_waitcnt lgkmcnt(1)
	v_mfma_f32_16x16x32_bf16 v[148:151], v[66:69], v[24:27], 0
	ds_read_b64_tr_b16 v[64:65], v22 offset:32256
	ds_read_b64_tr_b16 v[24:25], v22 offset:27680
	ds_read_b64_tr_b16 v[152:153], v22 offset:27712
	s_waitcnt lgkmcnt(2)
	v_mfma_f32_16x16x32_bf16 v[78:81], v[62:65], v[18:21], v[32:35]
	s_nop 2
	v_add_f32_e32 v32, 0, v56
	v_add_f32_e32 v32, v57, v32
	v_add_f32_e32 v32, v74, v32
	v_add_f32_e32 v32, v75, v32
	v_mfma_f32_16x16x32_bf16 v[120:123], v[70:73], v[28:31], 0
	v_add_f32_e32 v32, v76, v32
	v_add_f32_e32 v32, v106, v32
	v_add_f32_e32 v32, v108, v32
	v_mfma_f32_16x16x32_bf16 v[168:171], v[66:69], v[28:31], 0
	ds_read_b64_tr_b16 v[28:29], v22 offset:27744
	ds_read_b64_tr_b16 v[26:27], v22 offset:32288
	ds_read_b64_tr_b16 v[154:155], v22 offset:32320
	ds_read_b64_tr_b16 v[30:31], v22 offset:32352
	v_add_f32_e32 v32, v110, v32
	s_waitcnt lgkmcnt(2)
	v_mfma_f32_16x16x32_bf16 v[74:77], v[24:27], v[18:21], v[40:43]
	v_mfma_f32_16x16x32_bf16 v[70:73], v[24:27], v[112:115], v[44:47]
	v_add_f32_e32 v24, v111, v32
	v_add_f32_e32 v24, v156, v24
	v_add_f32_e32 v24, v157, v24
	v_add_f32_e32 v24, v164, v24
	v_add_f32_e32 v24, v165, v24
	v_add_f32_e32 v24, v166, v24
	v_mfma_f32_16x16x32_bf16 v[82:85], v[62:65], v[112:115], v[36:39]
	s_nop 2
	v_add_f32_e32 v36, v167, v24
	s_waitcnt lgkmcnt(1)
	v_mfma_f32_16x16x32_bf16 v[66:69], v[152:155], v[18:21], v[48:51]
	ds_read_b64_tr_b16 v[24:25], v22 offset:27776
	ds_read_b64_tr_b16 v[26:27], v22 offset:32384
	v_mfma_f32_16x16x32_bf16 v[62:65], v[152:155], v[112:115], v[52:55]
	s_waitcnt lgkmcnt(2)
	v_mfma_f32_16x16x32_bf16 v[54:57], v[28:31], v[18:21], v[116:119]
	ds_read_b64_tr_b16 v[32:33], v22 offset:27808
	s_nop 1
	ds_read_b64_tr_b16 v[116:117], v22 offset:27840
	ds_read_b64_tr_b16 v[152:153], v22 offset:27872
	ds_read_b64_tr_b16 v[34:35], v22 offset:32416
	ds_read_b64_tr_b16 v[118:119], v22 offset:32448
	ds_read_b64_tr_b16 v[154:155], v22 offset:32480
	v_add_f32_e32 v22, v183, v36
	v_pk_add_f32 v[166:167], v[22:23], 0 op_sel_hi:[1,0]
	v_add_f32_e32 v22, 0, v202
	v_add_f32_e32 v22, v203, v22
	v_add_f32_e32 v22, v212, v22
	v_add_f32_e32 v22, v213, v22
	v_add_f32_e32 v22, v214, v22
	v_add_f32_e32 v22, v215, v22
	v_add_f32_e32 v22, v216, v22
	v_add_f32_e32 v22, v217, v22
	v_add_f32_e32 v22, v218, v22
	v_add_f32_e32 v22, v219, v22
	v_add_f32_e32 v22, v220, v22
	v_add_f32_e32 v22, v221, v22
	v_add_f32_e32 v22, v222, v22
	v_add_f32_e32 v22, v223, v22
	v_add_f32_e32 v108, v224, v22
	v_mfma_f32_16x16x32_bf16 v[50:53], v[28:31], v[112:115], v[120:123]
	v_add_f32_e32 v108, v225, v108
	v_pk_add_f32 v[164:165], v[108:109], 0 op_sel_hi:[1,0]
	v_xor_b32_e32 v106, 0x80000000, v167
	s_waitcnt lgkmcnt(6)
	v_mfma_f32_16x16x32_bf16 v[46:49], v[24:27], v[18:21], v[124:127]
	v_xor_b32_e32 v110, 0x80000000, v165
	v_lshlrev_b32_e32 v183, 1, v107
	v_mov_b32_e32 v111, v110
	v_mfma_f32_16x16x32_bf16 v[42:45], v[24:27], v[112:115], v[128:131]
	v_mov_b32_e32 v107, v106
	v_mov_b32_e32 v108, v106
	v_mov_b32_e32 v109, v106
	s_waitcnt lgkmcnt(2)
	v_mfma_f32_16x16x32_bf16 v[38:41], v[32:35], v[18:21], v[132:135]
	s_waitcnt lgkmcnt(0)
	s_barrier
	v_mfma_f32_16x16x32_bf16 v[34:37], v[32:35], v[112:115], v[136:139]
	v_mfma_f32_16x16x32_bf16 v[30:33], v[116:119], v[18:21], v[140:143]
	v_mfma_f32_16x16x32_bf16 v[26:29], v[116:119], v[112:115], v[144:147]
	v_mfma_f32_16x16x32_bf16 v[22:25], v[152:155], v[18:21], v[148:151]
	v_mfma_f32_16x16x32_bf16 v[18:21], v[152:155], v[112:115], v[168:171]
	v_mov_b32_e32 v112, v110
	v_mov_b32_e32 v113, v110
	s_nop 0
	v_lshl_add_u64 v[168:169], s[4:5], 0, v[58:59]
	v_mad_i64_i32 v[58:59], s[8:9], s14, v192, v[94:95]
	v_lshl_add_u64 v[58:59], v[58:59], 0, v[96:97]
	v_lshl_add_u64 v[170:171], s[4:5], 0, v[58:59]
	s_mov_b64 s[8:9], 0
	v_subrev_u32_e32 v236, s4, v168
	v_subrev_u32_e32 v237, s4, v170
	v_add_u32_e32 v238, 0x1200000, v236
	v_add_u32_e32 v239, 0x1200000, v237
	s_add_u32 s34, s4, 0x1810c000
	s_addc_u32 s35, s5, 0
	s_branch .LBB0_125
